# adds Down epilogue load hoist; XCD tile remap guarded by fast-path flag
# baseline (speedup 1.0000x reference)
;     __device__ bool next(int i, Unit& u) const {
;         int mt, pn;
;         if ((G & 7) == 0 && (G >> 3) % nN == 0) { const int xcd = c & 7, j = c >> 3, per = (G >> 3) / nN; pn = j % nN; mt = (i * per + j / nN) * 8 + xcd; }
;         else { const int L = i * G + c; mt = L / nN; pn = L % nN; }
;         if (mt >= MT) return false;
;         u.pm = mt; u.pn = pn; int e = 0;
;         for (int j = 1; j < NEXP; ++j) e += (mpre[j] <= mt) ? 1 : 0;
;         u.e = __builtin_amdgcn_readfirstlane(e); return true;
;     }
.LBB0_26:
	s_or_b64 exec, exec, s[0:1]
	v_readlane_b32 s0, v253, 63
	s_waitcnt lgkmcnt(0)
	s_barrier
	v_mov_b32_e32 v0, s0
	v_readlane_b32 s0, v249, 49
	s_and_b32 s0, s0, 31
	ds_read_b32 v0, v0
	s_cmp_lg_u32 s0, 0
	s_cselect_b64 s[16:17], -1, 0
	v_writelane_b32 v249, s16, 50
	s_cmp_eq_u32 s0, 0
	v_readlane_b32 s0, v251, 29
	v_writelane_b32 v249, s17, 51
	s_cselect_b64 s[16:17], -1, 0
	s_and_b64 s[20:21], s[16:17], exec
	v_readlane_b32 s1, v251, 31
	s_waitcnt lgkmcnt(0)
	v_readfirstlane_b32 s15, v0
	s_cselect_b32 s40, s1, s0
	s_and_b64 vcc, exec, s[16:17]
	s_cbranch_vccz .Lxf_skip_d1
	s_lshr_b32 s98, s40, 3
	s_and_b32 s99, s40, 7
	s_add_i32 s100, s15, 7
	s_lshr_b32 s100, s100, 3
	s_mul_i32 s99, s99, s100
	s_add_i32 s40, s99, s98
	s_cmp_ge_u32 s98, s100
	s_cselect_b32 s40, 0x7fffffff, s40
.Lxf_skip_d1:
	s_cmp_lt_i32 s40, s15
	s_cselect_b64 s[20:21], -1, 0
	s_cmp_ge_i32 s40, s15
	v_readfirstlane_b32 s12, v168
	s_cbranch_scc1 .LBB0_28
	v_readlane_b32 s0, v254, 0
	s_nop 1
	v_mov_b32_e32 v0, s0
	ds_read2_b32 v[0:1], v0 offset1:1
	v_readlane_b32 s0, v254, 1
	s_waitcnt lgkmcnt(0)
	v_cmp_ge_i32_e32 vcc, s40, v0
	v_mov_b32_e32 v0, s0
	s_nop 0
	v_cndmask_b32_e64 v2, 0, 1, vcc
	v_cmp_ge_i32_e32 vcc, s40, v1
	ds_read2_b32 v[0:1], v0 offset1:1
	v_readlane_b32 s0, v254, 2
	v_cndmask_b32_e64 v3, 0, 1, vcc
	s_waitcnt lgkmcnt(0)
	v_cmp_ge_i32_e32 vcc, s40, v0
	s_nop 1
	v_addc_co_u32_e32 v2, vcc, v3, v2, vcc
	v_mov_b32_e32 v0, s0
	v_cmp_ge_i32_e32 vcc, s40, v1
	ds_read2_b32 v[0:1], v0 offset1:1
	v_readlane_b32 s0, v254, 3
	v_cndmask_b32_e64 v3, 0, 1, vcc
	s_waitcnt lgkmcnt(0)
	v_cmp_ge_i32_e32 vcc, s40, v0
	s_nop 1
	v_addc_co_u32_e32 v2, vcc, v2, v3, vcc
	v_mov_b32_e32 v0, s0
	v_cmp_ge_i32_e32 vcc, s40, v1
	ds_read2_b32 v[0:1], v0 offset1:1
	v_readlane_b32 s0, v254, 4
	v_cndmask_b32_e64 v3, 0, 1, vcc
	s_waitcnt lgkmcnt(0)
	v_cmp_ge_i32_e32 vcc, s40, v0
	s_nop 1
	v_addc_co_u32_e32 v2, vcc, v2, v3, vcc
	v_mov_b32_e32 v0, s0
	v_cmp_ge_i32_e32 vcc, s40, v1
	ds_read2_b32 v[0:1], v0 offset1:1
	v_readlane_b32 s0, v254, 5
	v_cndmask_b32_e64 v3, 0, 1, vcc
	s_waitcnt lgkmcnt(0)
	v_cmp_ge_i32_e32 vcc, s40, v0
	s_nop 1
	v_addc_co_u32_e32 v2, vcc, v2, v3, vcc
	v_mov_b32_e32 v0, s0
	v_cmp_ge_i32_e32 vcc, s40, v1
	ds_read2_b32 v[0:1], v0 offset1:1
	v_readlane_b32 s0, v254, 6
	v_cndmask_b32_e64 v3, 0, 1, vcc
	s_waitcnt lgkmcnt(0)
	v_cmp_ge_i32_e32 vcc, s40, v0
	s_nop 1
	v_addc_co_u32_e32 v2, vcc, v2, v3, vcc
	v_mov_b32_e32 v0, s0
	v_cmp_ge_i32_e32 vcc, s40, v1
	ds_read2_b32 v[0:1], v0 offset1:1
	v_readlane_b32 s0, v254, 7
	v_cndmask_b32_e64 v3, 0, 1, vcc
	s_waitcnt lgkmcnt(0)
	v_cmp_ge_i32_e32 vcc, s40, v0
	s_nop 1
	v_addc_co_u32_e32 v2, vcc, v2, v3, vcc
	v_mov_b32_e32 v0, s0
	v_cmp_ge_i32_e32 vcc, s40, v1
	ds_read2_b32 v[0:1], v0 offset1:1
	v_readlane_b32 s0, v254, 8
	v_cndmask_b32_e64 v3, 0, 1, vcc
	s_waitcnt lgkmcnt(0)
	v_cmp_ge_i32_e32 vcc, s40, v0
	s_nop 1
	v_addc_co_u32_e32 v2, vcc, v2, v3, vcc
	v_mov_b32_e32 v0, s0
	v_cmp_ge_i32_e32 vcc, s40, v1
	ds_read2_b32 v[0:1], v0 offset1:1
	v_readlane_b32 s0, v254, 9
	v_cndmask_b32_e64 v3, 0, 1, vcc
	s_waitcnt lgkmcnt(0)
	v_cmp_ge_i32_e32 vcc, s40, v0
	s_nop 1
	v_addc_co_u32_e32 v2, vcc, v2, v3, vcc
	v_mov_b32_e32 v0, s0
	v_cmp_ge_i32_e32 vcc, s40, v1
	ds_read2_b32 v[0:1], v0 offset1:1
	v_readlane_b32 s0, v254, 10
	v_cndmask_b32_e64 v3, 0, 1, vcc
	s_waitcnt lgkmcnt(0)
	v_cmp_ge_i32_e32 vcc, s40, v0
	s_nop 1
	v_addc_co_u32_e32 v2, vcc, v2, v3, vcc
	v_mov_b32_e32 v0, s0
	v_cmp_ge_i32_e32 vcc, s40, v1
	ds_read2_b32 v[0:1], v0 offset1:1
	v_readlane_b32 s0, v254, 11
	v_cndmask_b32_e64 v3, 0, 1, vcc
	s_waitcnt lgkmcnt(0)
	v_cmp_ge_i32_e32 vcc, s40, v0
	s_nop 1
	v_addc_co_u32_e32 v2, vcc, v2, v3, vcc
	v_mov_b32_e32 v0, s0
	v_cmp_ge_i32_e32 vcc, s40, v1
	ds_read2_b32 v[0:1], v0 offset1:1
	v_readlane_b32 s0, v254, 12
	v_cndmask_b32_e64 v3, 0, 1, vcc
	s_waitcnt lgkmcnt(0)
	v_cmp_ge_i32_e32 vcc, s40, v0
	s_nop 1
	v_addc_co_u32_e32 v2, vcc, v2, v3, vcc
	v_mov_b32_e32 v0, s0
	v_cmp_ge_i32_e32 vcc, s40, v1
	ds_read2_b32 v[0:1], v0 offset1:1
	v_readlane_b32 s0, v254, 13
	v_cndmask_b32_e64 v3, 0, 1, vcc
	s_waitcnt lgkmcnt(0)
	v_cmp_ge_i32_e32 vcc, s40, v0
	s_nop 1
	v_addc_co_u32_e32 v2, vcc, v2, v3, vcc
	v_mov_b32_e32 v0, s0
	v_cmp_ge_i32_e32 vcc, s40, v1
	ds_read2_b32 v[0:1], v0 offset1:1
	v_readlane_b32 s0, v254, 14
	v_cndmask_b32_e64 v3, 0, 1, vcc
	s_waitcnt lgkmcnt(0)
	v_cmp_ge_i32_e32 vcc, s40, v0
	s_nop 1
	v_addc_co_u32_e32 v2, vcc, v2, v3, vcc
	v_mov_b32_e32 v0, s0
	v_cmp_ge_i32_e32 vcc, s40, v1
	ds_read2_b32 v[0:1], v0 offset1:1
	v_readlane_b32 s0, v254, 15
	v_cndmask_b32_e64 v3, 0, 1, vcc
	s_waitcnt lgkmcnt(0)
	v_cmp_ge_i32_e32 vcc, s40, v0
	s_nop 1
	v_addc_co_u32_e32 v0, vcc, v2, v3, vcc
	v_mov_b32_e32 v2, s0
	ds_read_b32 v2, v2
	v_cmp_ge_i32_e32 vcc, s40, v1
	s_nop 1
	v_cndmask_b32_e64 v1, 0, 1, vcc
	s_waitcnt lgkmcnt(0)
	v_cmp_ge_i32_e32 vcc, s40, v2
	s_nop 1
	v_addc_co_u32_e32 v0, vcc, v0, v1, vcc
	s_nop 0
	v_readfirstlane_b32 s56, v0

; #define LAS __attribute__((address_space(3)))
; __device__ __forceinline__ unsigned pk2(float lo, float hi) { unsigned r; asm("v_cvt_pk_bf16_f32 %0, %1, %2" : "=v"(r) : "v"(lo), "v"(hi)); return r; }
;     __device__ __forceinline__ void operator()(const f32x4 (&acc)[2][2][4][2], const Unit& u, int wr, int wc, int fr, int fq, const LAS float* lb) const {
;         const int rl0 = wr * 64 + fr, col0 = u.pn * BM + wc * 32 + 8 * fq;
;         const int nvalid = cnt[u.e] - (u.pm - mpre[u.e]) * BM;
;         const float* be = bdn + (size_t)u.e * 1024;
;         f32x4 bv[2][2];
; #pragma unroll
;         for (int bj = 0; bj < 2; ++bj)
; #pragma unroll
;             for (int n = 0; n < 2; ++n) bv[bj][n] = *(const f32x4*)(be + col0 + bj * HALF + 4 * n);
;         int slots[2][4]; float gts[2][4];
; #pragma unroll
;         for (int ai = 0; ai < 2; ++ai)
; #pragma unroll
;             for (int m = 0; m < 4; ++m) { slots[ai][m] = rowslot[u.pm * BM + rl0 + ai * HALF + m * 16]; gts[ai][m] = slotg[u.pm * BM + rl0 + ai * HALF + m * 16]; }
; #pragma unroll
;         for (int ai = 0; ai < 2; ++ai)
; #pragma unroll
;             for (int m = 0; m < 4; ++m) { const int rl = rl0 + ai * HALF + m * 16;
;                 if (rl < nvalid) { const int slot = slots[ai][m]; const float g = gts[ai][m]; bf16_t* rowp = Y + (size_t)slot * 1024 + col0;
; #pragma unroll
;                     for (int bj = 0; bj < 2; ++bj) { const f32x4 v0 = (acc[ai][bj][m][0] * (1.0f / (W8_SCALE * ACT8_SCALE)) + bv[bj][0]) * g, v1 = (acc[ai][bj][m][1] * (1.0f / (W8_SCALE * ACT8_SCALE)) + bv[bj][1]) * g;
;                         u32x4 w; w.x = pk2(v0[0], v0[1]); w.y = pk2(v0[2], v0[3]); w.z = pk2(v1[0], v1[1]); w.w = pk2(v1[2], v1[3]);
;                         *(u32x4*)(rowp + bj * HALF) = w; } } }
.LBB0_45:
	v_mov_b32_e32 v18, v168
	s_lshl_b32 s0, s58, 8
	v_lshrrev_b32_e32 v0, 1, v18
	s_ashr_i32 s57, s56, 31
	v_and_or_b32 v0, v0, 24, s0
	s_lshl_b64 s[0:1], s[56:57], 2
	v_readlane_b32 s20, v254, 49
	v_readlane_b32 s21, v254, 50
	s_add_u32 s0, s20, s0
	s_addc_u32 s1, s21, s1
	global_load_dword v27, v33, s[0:1]
	s_lshl_b32 s0, s56, 2
	v_and_or_b32 v19, v18, 15, s66
	s_add_i32 s0, s0, 0
	v_lshl_add_u32 v20, s40, 8, v19
	s_add_i32 s12, s0, 0x20000
	s_lshl_b64 s[0:1], s[56:57], 12
	v_readlane_b32 s17, v254, 53
	v_or_b32_e32 v22, 16, v20
	v_or_b32_e32 v16, s67, v0
	s_add_u32 s0, s17, s0
	v_readlane_b32 s17, v254, 54
	v_ashrrev_i32_e32 v23, 31, v22
	v_readlane_b32 s22, v251, 25
	v_readlane_b32 s20, v251, 27
	s_addc_u32 s1, s17, s1
	v_ashrrev_i32_e32 v17, 31, v16
	v_lshlrev_b64 v[22:23], 2, v[22:23]
	v_readlane_b32 s23, v251, 26
	v_readlane_b32 s21, v251, 28
	v_lshl_add_u64 v[4:5], v[16:17], 2, s[0:1]
	v_lshl_add_u64 v[24:25], s[22:23], 0, v[22:23]
	v_lshl_add_u64 v[22:23], s[20:21], 0, v[22:23]
	global_load_dwordx4 v[8:11], v[4:5], off offset:16
	global_load_dwordx4 v[12:15], v[4:5], off
	global_load_dwordx4 v[0:3], v[4:5], off offset:528
	s_nop 0
	global_load_dwordx4 v[4:7], v[4:5], off offset:512
	v_ashrrev_i32_e32 v21, 31, v20
	global_load_dword v194, v[24:25], off
	global_load_dword v192, v[22:23], off
	v_or_b32_e32 v22, 32, v20
	v_ashrrev_i32_e32 v23, 31, v22
	v_lshlrev_b64 v[22:23], 2, v[22:23]
	v_lshl_add_u64 v[24:25], s[22:23], 0, v[22:23]
	v_lshl_add_u64 v[22:23], s[20:21], 0, v[22:23]
	global_load_dword v190, v[24:25], off
	global_load_dword v188, v[22:23], off
	v_or_b32_e32 v22, 48, v20
	v_ashrrev_i32_e32 v23, 31, v22
	v_lshlrev_b64 v[22:23], 2, v[22:23]
	v_lshlrev_b64 v[196:197], 2, v[20:21]
	s_mov_b64 s[0:1], 0x200
	v_lshl_add_u64 v[24:25], s[22:23], 0, v[22:23]
	v_lshl_add_u64 v[22:23], s[20:21], 0, v[22:23]
	v_lshl_add_u64 v[20:21], v[196:197], 0, s[0:1]
	global_load_dword v186, v[24:25], off
	global_load_dword v184, v[22:23], off
	v_lshl_add_u64 v[22:23], s[22:23], 0, v[20:21]
	v_lshl_add_u64 v[20:21], s[20:21], 0, v[20:21]
	s_mov_b64 s[0:1], 0x240
	global_load_dword v182, v[22:23], off
	global_load_dword v30, v[20:21], off
	v_lshl_add_u64 v[20:21], v[196:197], 0, s[0:1]
	v_lshl_add_u64 v[22:23], s[22:23], 0, v[20:21]
	v_lshl_add_u64 v[20:21], s[20:21], 0, v[20:21]
	s_mov_b64 s[0:1], 0x280
	global_load_dword v28, v[22:23], off
	global_load_dword v26, v[20:21], off
	v_lshl_add_u64 v[20:21], v[196:197], 0, s[0:1]
	s_mov_b64 s[0:1], 0x2c0
	v_lshl_add_u64 v[22:23], s[22:23], 0, v[20:21]
	v_lshl_add_u64 v[20:21], s[20:21], 0, v[20:21]
	v_lshl_add_u64 v[164:165], v[196:197], 0, s[0:1]
	global_load_dword v24, v[22:23], off
	s_nop 0
	global_load_dword v22, v[20:21], off
	v_lshl_add_u64 v[20:21], s[22:23], 0, v[164:165]
	v_lshl_add_u64 v[164:165], s[20:21], 0, v[164:165]
	global_load_dword v20, v[20:21], off
	s_nop 0
	global_load_dword v18, v[164:165], off
	v_mov_b32_e32 v21, s12
	ds_read_b32 v21, v21
	s_waitcnt lgkmcnt(0)
	v_subrev_u32_e32 v21, s40, v21
	v_lshlrev_b32_e32 v21, 8, v21
	v_readlane_b32 s0, v251, 27
	v_readlane_b32 s1, v251, 28
	s_nop 0
	v_lshl_add_u64 v[164:165], s[0:1], 0, v[196:197]
	v_lshl_add_u64 v[196:197], s[22:23], 0, v[196:197]
	global_load_dword v164, v[164:165], off
	global_load_dword v196, v[196:197], off
	s_waitcnt vmcnt(0)
	v_add_u32_e32 v21, v21, v27
	v_cmp_lt_i32_e32 vcc, v19, v21
	s_and_saveexec_b64 s[20:21], vcc
	s_mov_b32 s12, 0x3b000000
	s_cbranch_execz .LBB0_47
	v_readlane_b32 s0, v251, 27
	v_readlane_b32 s1, v251, 28
	v_pk_fma_f32 v[162:163], v[162:163], s[12:13], v[14:15] op_sel_hi:[1,0,1]
	v_pk_fma_f32 v[160:161], v[160:161], s[12:13], v[12:13] op_sel_hi:[1,0,1]
	v_pk_fma_f32 v[158:159], v[158:159], s[12:13], v[10:11] op_sel_hi:[1,0,1]
	v_pk_fma_f32 v[156:157], v[156:157], s[12:13], v[8:9] op_sel_hi:[1,0,1]
	v_pk_fma_f32 v[150:151], v[150:151], s[12:13], v[2:3] op_sel_hi:[1,0,1]
	v_pk_fma_f32 v[148:149], v[148:149], s[12:13], v[0:1] op_sel_hi:[1,0,1]
	v_pk_fma_f32 v[154:155], v[154:155], s[12:13], v[6:7] op_sel_hi:[1,0,1]
	v_pk_fma_f32 v[152:153], v[152:153], s[12:13], v[4:5] op_sel_hi:[1,0,1]
	s_waitcnt vmcnt(1)
	v_pk_mul_f32 v[162:163], v[162:163], v[164:165] op_sel_hi:[1,0]
	v_pk_mul_f32 v[160:161], v[160:161], v[164:165] op_sel_hi:[1,0]
	s_waitcnt vmcnt(0)
	v_ashrrev_i32_e32 v197, 31, v196
	v_lshlrev_b64 v[196:197], 11, v[196:197]
	v_lshl_add_u64 v[196:197], s[96:97], 0, v[196:197]
	v_lshl_add_u64 v[196:197], v[16:17], 1, v[196:197]
	v_pk_mul_f32 v[198:199], v[158:159], v[164:165] op_sel_hi:[1,0]
	v_pk_mul_f32 v[158:159], v[156:157], v[164:165] op_sel_hi:[1,0]
	v_cvt_pk_bf16_f32 v156, v160, v161
	v_cvt_pk_bf16_f32 v157, v162, v163
	v_pk_mul_f32 v[154:155], v[154:155], v[164:165] op_sel_hi:[1,0]
	v_cvt_pk_bf16_f32 v158, v158, v159
	v_cvt_pk_bf16_f32 v159, v198, v199
	global_store_dwordx4 v[196:197], v[156:159], off
	v_pk_mul_f32 v[152:153], v[152:153], v[164:165] op_sel_hi:[1,0]
	s_nop 0
	v_pk_mul_f32 v[156:157], v[150:151], v[164:165] op_sel_hi:[1,0]
	v_pk_mul_f32 v[150:151], v[148:149], v[164:165] op_sel_hi:[1,0]
	v_cvt_pk_bf16_f32 v148, v152, v153
	v_cvt_pk_bf16_f32 v149, v154, v155
	s_nop 0
	v_cvt_pk_bf16_f32 v150, v150, v151
	v_cvt_pk_bf16_f32 v151, v156, v157
	global_store_dwordx4 v[196:197], v[148:151], off offset:256

;     __device__ bool next(int i, Unit& u) const {
;     ...
;         if ((G & 7) == 0 && (G >> 3) % nN == 0) { const int xcd = c & 7, j = c >> 3, per = (G >> 3) / nN; pn = j % nN; mt = (i * per + j / nN) * 8 + xcd; }
;         else { const int L = i * G + c; mt = L / nN; pn = L % nN; }
;         if (mt >= MT) return false;
; __device__ __forceinline__ void run_phase(const Args& a, const int ph, LAS unsigned char* lds, const int tid, const int rpt) {
;     ...
;                   __syncthreads(); S.rt = RT; }
.LBB0_81:
	s_or_b64 exec, exec, s[0:1]
	s_cmp_lg_u32 s12, 0
	s_cselect_b64 s[0:1], -1, 0
	s_cmp_eq_u32 s12, 0
	s_cselect_b64 s[16:17], -1, 0
	s_and_b64 s[20:21], s[16:17], exec
	v_readlane_b32 s12, v253, 28
	v_readlane_b32 s20, v251, 38
	s_cselect_b32 s93, s20, s12
	s_and_b64 vcc, exec, s[16:17]
	s_cbranch_vccz .Lxf_skip_g1
	s_lshr_b32 s98, s93, 3
	s_and_b32 s99, s93, 7
	s_add_i32 s100, s15, 7
	s_lshr_b32 s100, s100, 3
	s_mul_i32 s99, s99, s100
	s_add_i32 s93, s99, s98
	s_cmp_ge_u32 s98, s100
	s_cselect_b32 s93, 0x7fffffff, s93
; #define PG8_LOADOFF(dst, round) do { _Pragma("unroll") for (int _i = 0; _i < 2; ++_i) \
;         _Pragma("unroll") for (int _h = 0; _h < 2; ++_h) dst[_h][_i] = GATHER ? ((unsigned)S.rt[(round) * 256 + _h * 128 + _i * 64 + R0] * (unsigned)(K * 2) + (unsigned)(C0 * 2)) : voffA[_i]; } while (0)
; template <bool GATHER, bool FP8, class Epi, class Sched>
; __device__ __forceinline__ void gemm_phase(LAS unsigned char* lds, const int tid, const int K, const Sched& S, const Epi& E) {
;     const int wid = __builtin_amdgcn_readfirstlane(tid >> 6), lane = tid & 63, wr = wid >> 2, wc = wid & 3, fr = lane & 15, fq = lane >> 4;
;     const int nt = K / BK;
;     int R0, C0; stage_rc(tid * 16, R0, C0); const int Rb0 = Epi::PERM ? ((R0 & ~31) + perm32(R0 & 31)) : R0;
;     unsigned voffA[2], voffB[2];
;     voffA[0] = (unsigned)(R0 * K + C0) * 2u; voffA[1] = voffA[0] + (unsigned)(64 * K * 2);
;     voffB[0] = (unsigned)(Rb0 * 128 + C0 * 2); voffB[1] = voffB[0] + 64u * 128u;
;     const size_t kstepB = 32768, hstepB = 16384;
;     const size_t kstep = (size_t)(BK * 2);
;     const size_t hstep = (size_t)HALF * K * 2;
;     const size_t hsA = GATHER ? (size_t)0 : hstep;
;     unsigned oC[2][2], o2[2][2];
;     ...
;     const unsigned ldsw = (unsigned)wid * 1024u;
;     const int aoff = lds_byte(wr * 64 + fr, fq * 8), boff = lds_byte(wc * 32 + fr, fq * 8);
;     ...
;     Unit cur, nxt; int ui = 0;
;     if (!S.next(0, cur)) return;
;     int sc8 = 0x7f; asm volatile("" : "+v"(sc8));
;     float zf = 0.f; asm volatile("" : "+v"(zf));
;     f32x4 acc[2][2][4][2];
; #pragma unroll
;     for (int a = 0; a < 2; ++a)
; #pragma unroll
;         for (int b = 0; b < 2; ++b)
; #pragma unroll
;             for (int m = 0; m < 4; ++m)
; #pragma unroll
;                 for (int n = 0; n < 2; ++n) acc[a][b][m][n] = (f32x4){zf, zf, zf, zf};
;     bf16x8 At[4][2], B0[2][2], B1[2][2];
;     i32x8 At8[4], B08[2], B18[2];
;     const char* cA = S.aptr(cur); const char* cB = S.bptr(cur);
;     PG8_LOADOFF(oC, 0);
; #pragma unroll
;     for (int _h = 0; _h < 2; ++_h)
; #pragma unroll
;         for (int _i = 0; _i < 2; ++_i) o2[_h][_i] = oC[_h][_i];
;     PG8_STAGE(PG8_SB(0, 0), cB, voffB); PG8_STAGE(PG8_SB(0, 1), cB + hstepB, voffB); PG8_STAGE(PG8_SA(0, 0), cA, oC[0]); PG8_STAGE(PG8_SA(0, 1), cA + hsA, oC[1]);
.Lxf_skip_g1:
	s_cmp_ge_i32 s93, s15
	v_readfirstlane_b32 s12, v168
	s_waitcnt lgkmcnt(0)
	s_barrier
	s_cbranch_scc1 .LBB0_105
	v_bfe_i32 v2, v168, 27, 1
	v_lshlrev_b32_e32 v0, 4, v168
	v_lshrrev_b32_e32 v2, 22, v2
	v_add_u32_e32 v2, v0, v2
	v_and_b32_e32 v2, 0xfffffc00, v2
	s_ashr_i32 s27, s12, 6
	v_sub_u32_e32 v0, v0, v2
	s_ashr_i32 s26, s12, 8
	v_lshrrev_b32_e32 v2, 4, v0
	s_lshl_b32 s36, s27, 10
	v_bitop3_b32 v0, v2, v0, 32 bitop3:0x6c
	s_and_b64 s[16:17], s[16:17], exec
	v_ashrrev_i32_e32 v3, 31, v0
	v_readlane_b32 s16, v251, 12
	v_readlane_b32 s17, v251, 34
	v_ashrrev_i32_e32 v1, 31, v168
	v_lshrrev_b32_e32 v3, 26, v3
	s_cselect_b32 s16, s17, s16
	v_lshrrev_b32_e32 v1, 26, v1
	v_add_u32_e32 v3, v0, v3
	s_ashr_i32 s17, s16, 31
	v_add_u32_e32 v1, v168, v1
	v_ashrrev_i32_e32 v4, 6, v3
	v_and_b32_e32 v3, 0xc0, v3
	s_lshr_b32 s17, s17, 29
	v_ashrrev_i32_e32 v1, 6, v1
	v_sub_u32_e32 v0, v0, v3
	v_mov_b32_e32 v3, 1
	s_add_i32 s17, s16, s17
	v_lshlrev_b32_e32 v2, 5, v1
	v_ashrrev_i16_sdwa v0, v3, sext(v0) dst_sel:DWORD dst_unused:UNUSED_PAD src0_sel:DWORD src1_sel:BYTE_0
	s_and_b32 s17, s17, -8
	v_and_b32_e32 v2, 32, v2
	v_bfe_i32 v0, v0, 0, 16
	s_sub_i32 s46, s16, s17
	v_readlane_b32 s16, v254, 0
	v_add_lshl_u32 v39, v2, v0, 1
	v_lshlrev_b32_e32 v0, 3, v1
	v_mov_b32_e32 v1, s16
	ds_read2_b32 v[2:3], v1 offset1:1
	v_readlane_b32 s16, v254, 1
	v_and_b32_e32 v0, -16, v0
	v_add_u32_e32 v0, v4, v0
	v_lshl_add_u32 v172, v0, 7, v39
	s_waitcnt lgkmcnt(0)
	v_cmp_ge_i32_e32 vcc, s93, v2
	v_mov_b32_e32 v2, s16
	v_readlane_b32 s16, v254, 2
	v_cndmask_b32_e64 v1, 0, 1, vcc
	v_cmp_ge_i32_e32 vcc, s93, v3
	ds_read2_b32 v[2:3], v2 offset1:1
	v_lshl_add_u32 v0, v0, 1, 0
	v_cndmask_b32_e64 v4, 0, 1, vcc
	v_mov_b32_e32 v169, 0x7f
	v_mov_b32_e32 v186, v33
	s_waitcnt lgkmcnt(0)
	v_cmp_ge_i32_e32 vcc, s93, v2
	v_mov_b32_e32 v2, s16
	v_readlane_b32 s16, v254, 3
	v_addc_co_u32_e32 v1, vcc, v4, v1, vcc
	v_cmp_ge_i32_e32 vcc, s93, v3
	ds_read2_b32 v[2:3], v2 offset1:1
	v_add_u32_e32 v187, 0x20100, v0
	v_cndmask_b32_e64 v4, 0, 1, vcc
	s_ashr_i32 s47, s46, 31
	s_lshl_b64 s[22:23], s[46:47], 18
	s_waitcnt lgkmcnt(0)
	v_cmp_ge_i32_e32 vcc, s93, v2
	v_mov_b32_e32 v2, s16
	v_readlane_b32 s16, v254, 4
	v_addc_co_u32_e32 v1, vcc, v1, v4, vcc
	v_cmp_ge_i32_e32 vcc, s93, v3
	ds_read2_b32 v[2:3], v2 offset1:1
	v_add_u32_e32 v174, 0x2000, v172
	v_cndmask_b32_e64 v4, 0, 1, vcc
	v_writelane_b32 v249, s71, 53
	s_waitcnt lgkmcnt(0)
	v_cmp_ge_i32_e32 vcc, s93, v2
	v_mov_b32_e32 v2, s16
	s_nop 0
	v_addc_co_u32_e32 v1, vcc, v1, v4, vcc
	v_cmp_ge_i32_e32 vcc, s93, v3
	ds_read2_b32 v[2:3], v2 offset1:1
	v_readlane_b32 s16, v254, 5
	v_cndmask_b32_e64 v4, 0, 1, vcc
	s_waitcnt lgkmcnt(0)
	v_cmp_ge_i32_e32 vcc, s93, v2
	s_nop 1
	v_addc_co_u32_e32 v1, vcc, v1, v4, vcc
	v_mov_b32_e32 v2, s16
	v_cmp_ge_i32_e32 vcc, s93, v3
	ds_read2_b32 v[2:3], v2 offset1:1
	v_readlane_b32 s16, v254, 6
	v_cndmask_b32_e64 v4, 0, 1, vcc
	s_waitcnt lgkmcnt(0)
	v_cmp_ge_i32_e32 vcc, s93, v2
	s_nop 1
	v_addc_co_u32_e32 v1, vcc, v1, v4, vcc
	v_mov_b32_e32 v2, s16
	v_cmp_ge_i32_e32 vcc, s93, v3
	ds_read2_b32 v[2:3], v2 offset1:1
	v_readlane_b32 s16, v254, 7
	v_cndmask_b32_e64 v4, 0, 1, vcc
	s_waitcnt lgkmcnt(0)
	v_cmp_ge_i32_e32 vcc, s93, v2
	s_nop 1
	v_addc_co_u32_e32 v1, vcc, v1, v4, vcc
	v_mov_b32_e32 v2, s16
	v_cmp_ge_i32_e32 vcc, s93, v3
	ds_read2_b32 v[2:3], v2 offset1:1
	v_readlane_b32 s16, v254, 8
	v_cndmask_b32_e64 v4, 0, 1, vcc
	s_waitcnt lgkmcnt(0)
	v_cmp_ge_i32_e32 vcc, s93, v2
	s_nop 1
	v_addc_co_u32_e32 v1, vcc, v1, v4, vcc
	v_mov_b32_e32 v2, s16
	v_cmp_ge_i32_e32 vcc, s93, v3
	ds_read2_b32 v[2:3], v2 offset1:1
	v_readlane_b32 s16, v254, 9
	v_cndmask_b32_e64 v4, 0, 1, vcc
	s_waitcnt lgkmcnt(0)
	v_cmp_ge_i32_e32 vcc, s93, v2
	s_nop 1
	v_addc_co_u32_e32 v1, vcc, v1, v4, vcc
	v_mov_b32_e32 v2, s16
	v_cmp_ge_i32_e32 vcc, s93, v3
	ds_read2_b32 v[2:3], v2 offset1:1
	v_readlane_b32 s16, v254, 10
	v_cndmask_b32_e64 v4, 0, 1, vcc
	s_waitcnt lgkmcnt(0)
	v_cmp_ge_i32_e32 vcc, s93, v2
	s_nop 1
	v_addc_co_u32_e32 v1, vcc, v1, v4, vcc
	v_mov_b32_e32 v2, s16
	v_cmp_ge_i32_e32 vcc, s93, v3
	ds_read2_b32 v[2:3], v2 offset1:1
	v_readlane_b32 s16, v254, 11
	v_cndmask_b32_e64 v4, 0, 1, vcc
	s_waitcnt lgkmcnt(0)
	v_cmp_ge_i32_e32 vcc, s93, v2
	s_nop 1
	v_addc_co_u32_e32 v1, vcc, v1, v4, vcc
	v_mov_b32_e32 v2, s16
	v_cmp_ge_i32_e32 vcc, s93, v3
	ds_read2_b32 v[2:3], v2 offset1:1
	v_readlane_b32 s16, v254, 12
	v_cndmask_b32_e64 v4, 0, 1, vcc
	s_waitcnt lgkmcnt(0)
	v_cmp_ge_i32_e32 vcc, s93, v2
	s_nop 1
	v_addc_co_u32_e32 v1, vcc, v1, v4, vcc
	v_mov_b32_e32 v2, s16
	v_cmp_ge_i32_e32 vcc, s93, v3
	ds_read2_b32 v[2:3], v2 offset1:1
	v_readlane_b32 s16, v254, 13
	v_cndmask_b32_e64 v4, 0, 1, vcc
	s_waitcnt lgkmcnt(0)
	v_cmp_ge_i32_e32 vcc, s93, v2
	s_nop 1
	v_addc_co_u32_e32 v1, vcc, v1, v4, vcc
	v_mov_b32_e32 v2, s16
	v_cmp_ge_i32_e32 vcc, s93, v3
	ds_read2_b32 v[2:3], v2 offset1:1
	v_readlane_b32 s16, v254, 14
	v_cndmask_b32_e64 v4, 0, 1, vcc
	s_waitcnt lgkmcnt(0)
	v_cmp_ge_i32_e32 vcc, s93, v2
	s_nop 1
	v_addc_co_u32_e32 v1, vcc, v1, v4, vcc
	v_mov_b32_e32 v2, s16
	v_cmp_ge_i32_e32 vcc, s93, v3
	ds_read2_b32 v[2:3], v2 offset1:1
	v_readlane_b32 s16, v254, 15
	v_cndmask_b32_e64 v4, 0, 1, vcc
	s_waitcnt lgkmcnt(0)
	v_cmp_ge_i32_e32 vcc, s93, v2
	s_nop 1
	v_addc_co_u32_e32 v1, vcc, v1, v4, vcc
	v_cmp_ge_i32_e32 vcc, s93, v3
	v_mov_b32_e32 v3, s16
	ds_read_b32 v3, v3
	ds_read_u16 v0, v187
	v_cndmask_b32_e64 v2, 0, 1, vcc
	s_waitcnt lgkmcnt(0)
	v_cmp_ge_i32_e32 vcc, s93, v3
	s_waitcnt lgkmcnt(0)
	v_lshl_add_u32 v32, v0, 10, v39
	v_addc_co_u32_e32 v1, vcc, v1, v2, vcc
	ds_read_u16 v0, v187 offset:256
	v_readfirstlane_b32 s20, v1
	s_ashr_i32 s21, s20, 31
	s_lshl_b64 s[16:17], s[20:21], 21
	v_readlane_b32 s21, v254, 55
	s_add_u32 s16, s21, s16
	v_readlane_b32 s21, v254, 56
	s_waitcnt lgkmcnt(0)
	v_lshl_add_u32 v188, v0, 10, v39
	ds_read_u16 v0, v187 offset:128
	s_addc_u32 s17, s21, s17
	s_add_u32 s22, s16, s22
	s_addc_u32 s23, s17, s23
	s_add_i32 s47, s36, 0
	s_add_i32 s54, s47, 0x10000
	s_add_i32 s55, s47, 0x12000
	s_mov_b32 m0, s54
	s_add_u32 s16, s22, 0x4000
	s_waitcnt lgkmcnt(0)
	v_lshl_add_u32 v176, v0, 10, v39
	ds_read_u16 v0, v187 offset:384
	global_load_lds_dwordx4 v172, s[22:23]
	s_mov_b32 m0, s55
	s_addc_u32 s17, s23, 0
	s_add_i32 s56, s47, 0x14000
	global_load_lds_dwordx4 v174, s[22:23]
	s_mov_b32 m0, s56
	s_add_i32 s57, s47, 0x16000
	global_load_lds_dwordx4 v172, s[16:17]
	s_mov_b32 m0, s57
	s_add_i32 s58, s47, 0x2000
	global_load_lds_dwordx4 v174, s[16:17]
	s_mov_b32 m0, s47
	s_add_i32 s59, s47, 0x4000
	global_load_lds_dwordx4 v32, s[6:7]
	s_mov_b32 m0, s58
	s_add_i32 s60, s47, 0x6000
	global_load_lds_dwordx4 v176, s[6:7]
	s_mov_b32 m0, s59
	s_waitcnt lgkmcnt(0)
	v_lshl_add_u32 v190, v0, 10, v39
	global_load_lds_dwordx4 v188, s[6:7]
	s_mov_b32 m0, s60
	s_cmp_eq_u32 s26, 1
	global_load_lds_dwordx4 v190, s[6:7]
	s_cselect_b64 s[16:17], -1, 0
	v_writelane_b32 v249, s16, 54
	s_cmp_lg_u32 s26, 1
	s_nop 0
	v_writelane_b32 v249, s17, 55
	s_cbranch_scc1 .LBB0_84
	s_barrier
